# static priority raise mirrored: s_setprio 1 for workgroups < 256, all other s_setprio replaced by s_nop 0
# speedup vs baseline: 1.0022x; 1.0022x over previous
; #define LAS __attribute__((address_space(3)))
; DI unsigned xb_ld(unsigned* p)              { return __hip_atomic_load(p, __ATOMIC_RELAXED, __HIP_MEMORY_SCOPE_AGENT); }
; DI void xcd_barrier_complete(unsigned* bar, unsigned x, unsigned& nloc, unsigned& nx) {
;   const unsigned G = gridDim.x * gridDim.y * gridDim.z;
;   unsigned sum, cnt, mine, sp = 0u;
;   for (;;) {
;     sum = 0u; cnt = 0u; mine = 0u;
; #pragma unroll
;     for (unsigned j = 0; j < 16; ++j) { const unsigned c = xb_ld(&bar[XB_XCNT(j)]); sum += c; cnt += (c > 0u) ? 1u : 0u; mine = (j == x) ? c : mine; }
;     if (sum == G) break;
;     __builtin_amdgcn_s_sleep(1);
;     if ((++sp & 255u) == 0u) { if (xb_ld(&bar[XB_TMO])) break; if (sp > XB_SPIN_CAP) { atomicAdd(&bar[XB_TMO], 1u); break; } }
;   }
;   nloc = mine > 0u ? mine : 1u; nx = cnt > 0u ? cnt : 1u;
; __global__ void __launch_bounds__(256, 2) mega_kernel(Params p) {
;     ...
;   cg::grid_group grid = cg::this_grid();
;   if (threadIdx.x == 0) xb_words = make_uint4(0u, 0u, 0u, 0u);
;   __syncthreads();
;   const XcdBarrier xb = xcd_barrier_post((unsigned*)(p.ws + OFF_BAR), (volatile LAS unsigned*)&xb_words);
;   phase_prep(p, smem);
;   grid.sync();
; #pragma unroll 1
;   for (int step = 0; step < 2 + NCHUNK * 17; ++step) {
.LBB1_178:
	s_or_b64 exec, exec, s[0:1]
	s_mul_i32 s0, s79, s78
	s_lshl_b32 s56, s78, 2
	s_lshl_b32 s57, s78, 8
	s_mul_i32 s58, s0, s3
	s_add_u32 s0, s76, 0x1c140200
	s_addc_u32 s1, s77, 0
	v_writelane_b32 v254, s0, 34
	v_exp_f32_e32 v173, 0xbf549a78
	v_exp_f32_e32 v252, 0xbfd49a78
	v_writelane_b32 v254, s1, 35
	s_add_u32 s0, s76, 0x1c140400
	s_addc_u32 s1, s77, 0
	v_writelane_b32 v254, s0, 36
	v_exp_f32_e32 v253, 0xc01f73da
	v_exp_f32_e32 v192, 0xc0549a78
	v_writelane_b32 v254, s1, 37
	s_add_u32 s0, s76, 0x1c140500
	s_addc_u32 s1, s77, 0
	v_writelane_b32 v254, s0, 38
	v_exp_f32_e32 v195, 0xc084e08b
	v_exp_f32_e32 v178, 0xc09f73da
	v_writelane_b32 v254, s1, 39
	s_add_u32 s0, s76, 0x1c140600
	s_addc_u32 s1, s77, 0
	v_writelane_b32 v254, s0, 40
	v_exp_f32_e32 v179, 0xc0ba0729
	v_exp_f32_e32 v180, 0xc0d49a78
	v_writelane_b32 v254, s1, 41
	s_add_u32 s0, s76, 0x1c140700
	s_addc_u32 s1, s77, 0
	v_writelane_b32 v254, s0, 42
	v_exp_f32_e32 v181, 0xc0ef2dc7
	v_exp_f32_e32 v182, 0xc104e08b
	v_writelane_b32 v254, s1, 43
	s_add_u32 s0, s76, 0x1c140800
	s_addc_u32 s1, s77, 0
	s_add_u32 s62, s76, 0x1c140900
	s_addc_u32 s63, s77, 0
	s_add_u32 s64, s76, 0x1c140a00
	s_addc_u32 s65, s77, 0
	s_add_u32 s66, s76, 0x1c140b00
	s_addc_u32 s67, s77, 0
	s_add_u32 s68, s76, 0x1c140c00
	s_addc_u32 s69, s77, 0
	s_add_u32 s70, s76, 0x1c140d00
	s_addc_u32 s71, s77, 0
	s_add_u32 s72, s76, 0x1c140e00
	s_addc_u32 s73, s77, 0
	s_add_u32 s80, s76, 0x1c140f00
	s_addc_u32 s81, s77, 0
	s_add_u32 s82, s76, 0x1c141000
	s_addc_u32 s83, s77, 0
	s_add_u32 s84, s76, 0x1c141100
	s_addc_u32 s85, s77, 0
	s_add_u32 s86, s76, 0x1c141200
	s_addc_u32 s87, s77, 0
	s_add_u32 s88, s76, 0x1c141300
	s_addc_u32 s89, s77, 0
	v_writelane_b32 v254, s0, 44
	s_cmp_eq_u32 s2, 15
	v_exp_f32_e32 v183, 0xc1122a32
	v_writelane_b32 v254, s1, 45
	s_cselect_b64 s[0:1], -1, 0
	v_writelane_b32 v254, s0, 46
	s_cmp_eq_u32 s2, 14
	v_exp_f32_e32 v184, 0xc11f73da
	v_writelane_b32 v254, s1, 47
	s_cselect_b64 s[0:1], -1, 0
	v_writelane_b32 v254, s0, 48
	s_cmp_eq_u32 s2, 13
	v_exp_f32_e32 v185, 0xc12cbd82
	v_writelane_b32 v254, s1, 49
	s_cselect_b64 s[0:1], -1, 0
	v_writelane_b32 v254, s0, 50
	s_cmp_eq_u32 s2, 12
	v_exp_f32_e32 v186, 0xc13a0729
	v_writelane_b32 v254, s1, 51
	s_cselect_b64 s[0:1], -1, 0
	v_writelane_b32 v254, s0, 52
	s_cmp_eq_u32 s2, 11
	v_exp_f32_e32 v187, 0xc14750d0
	v_writelane_b32 v254, s1, 53
	s_cselect_b64 s[0:1], -1, 0
	v_writelane_b32 v254, s0, 54
	s_cmp_eq_u32 s2, 10
	v_mbcnt_lo_u32_b32 v0, -1, 0
	v_writelane_b32 v254, s1, 55
	s_cselect_b64 s[0:1], -1, 0
	v_writelane_b32 v254, s0, 56
	s_cmp_eq_u32 s2, 9
	v_mbcnt_hi_u32_b32 v193, -1, v0
	v_writelane_b32 v254, s1, 57
	s_cselect_b64 s[0:1], -1, 0
	v_writelane_b32 v254, s0, 58
	s_cmp_eq_u32 s2, 8
	v_and_b32_e32 v0, 64, v193
	v_writelane_b32 v254, s1, 59
	s_cselect_b64 s[0:1], -1, 0
	v_writelane_b32 v254, s0, 60
	s_cmp_eq_u32 s2, 7
	v_mov_b32_e32 v1, 0
	v_writelane_b32 v254, s1, 61
	s_cselect_b64 s[0:1], -1, 0
	v_writelane_b32 v254, s0, 62
	s_cmp_eq_u32 s2, 6
	s_movk_i32 s91, 0x48
	v_writelane_b32 v254, s1, 63
	s_cselect_b64 s[0:1], -1, 0
	v_writelane_b32 v255, s0, 0
	s_cmp_eq_u32 s2, 5
	s_mov_b32 s90, 0xfffffc0
	v_writelane_b32 v255, s1, 1
	s_cselect_b64 s[0:1], -1, 0
	v_writelane_b32 v255, s0, 2
	s_cmp_eq_u32 s2, 4
	s_movk_i32 s4, 0x90
	v_writelane_b32 v255, s1, 3
	s_cselect_b64 s[0:1], -1, 0
	v_writelane_b32 v255, s0, 4
	s_cmp_eq_u32 s2, 3
	s_movk_i32 s5, 0x210
	v_writelane_b32 v255, s1, 5
	s_cselect_b64 s[0:1], -1, 0
	v_writelane_b32 v255, s0, 6
	s_cmp_eq_u32 s2, 2
	s_movk_i32 s60, 0xf800
	v_writelane_b32 v255, s1, 7
	s_cselect_b64 s[0:1], -1, 0
	v_writelane_b32 v255, s0, 8
	s_cmp_eq_u32 s2, 1
	v_mov_b32_e32 v188, 0x358637bd
	v_writelane_b32 v255, s1, 9
	s_cselect_b64 s[0:1], -1, 0
	v_writelane_b32 v255, s0, 10
	s_cmp_eq_u32 s2, 0
	v_mov_b32_e32 v189, 0x12200
	v_writelane_b32 v255, s1, 11
	s_cselect_b64 s[0:1], -1, 0
	v_writelane_b32 v255, s0, 12
	v_mov_b32_e32 v190, 0x12204
	v_mov_b32_e32 v191, 1
	v_writelane_b32 v255, s1, 13
	s_lshl_b32 s0, s2, 8
	s_add_u32 s0, s20, s0
	s_addc_u32 s1, s21, 0
	s_add_u32 s2, s0, 0x1400
	s_addc_u32 s3, s1, 0
	v_writelane_b32 v255, s2, 14
	s_add_u32 s0, s0, 0x2400
	s_addc_u32 s1, s1, 0
	v_writelane_b32 v255, s3, 15
	v_writelane_b32 v255, s0, 16
	v_add_u32_e32 v194, 64, v0
	v_xor_b32_e32 v196, 16, v193
	v_writelane_b32 v255, s1, 17
	s_add_u32 s0, s76, 0x1c143400
	s_addc_u32 s1, s77, 0
	v_writelane_b32 v255, s0, 18
	v_xor_b32_e32 v197, 8, v193
	v_xor_b32_e32 v198, 4, v193
	v_writelane_b32 v255, s1, 19
	s_add_u32 s0, s76, 0x1c143500
	s_addc_u32 s1, s77, 0
	v_writelane_b32 v255, s0, 20
	s_lshl_b32 s59, s78, 17
	s_lshl_b32 s95, s78, 7
	v_writelane_b32 v255, s1, 21
	s_lshl_b32 s0, s78, 19
	v_writelane_b32 v255, s0, 22
	v_writelane_b32 v255, s92, 23
	v_writelane_b32 v255, s56, 24
	v_writelane_b32 v255, s57, 25
	v_writelane_b32 v255, s58, 26
	v_xor_b32_e32 v199, 2, v193
	v_xor_b32_e32 v200, 1, v193
	v_mov_b32_e32 v201, 0x12000
	v_mov_b32_e32 v202, 0xff800000
	v_mov_b32_e32 v203, 0xc0
	v_mov_b32_e32 v204, 0x12080
	v_mov_b32_e32 v205, 0x12100
	v_mov_b32_e32 v206, 0x12180
	v_mov_b32_e32 v207, 0x3e0293ee
	s_mov_b32 s38, 0x20000
	s_mov_b32 s39, 0x800000
	s_mov_b32 s96, 0x19140000
	s_mov_b32 s97, 0x2980000
	s_movk_i32 s3, 0x110
	s_mov_b32 s7, 0xff800000
	s_movk_i32 s33, 0x41
	s_mov_b32 s6, -1
	s_mov_b32 s1, 0
	s_mov_b64 s[8:9], 0x80
	s_mov_b64 s[10:11], 0x18000
	v_writelane_b32 v255, s59, 27
	s_cmp_ge_u32 s92, 0x100
	s_cbranch_scc1 .Lprio_done
	s_setprio 1
